# speedup vs baseline: 1.0099x; 1.0099x over previous
; #define SLOAD(i, k0) do { sr_[i].vs0 = *reinterpret_cast<const bf16x8*>(&Vh[(size_t)((k0) + sr) * LDQ + sc]); sr_[i].vs1 = *reinterpret_cast<const bf16x8*>(&Vh[(size_t)((k0) + 32 + sr) * LDQ + sc]); \
;     sr_[i].ks0 = *reinterpret_cast<const bf16x8*>(&Kh[(size_t)((k0) + sr) * LDQ + sc]); sr_[i].ks1 = *reinterpret_cast<const bf16x8*>(&Kh[(size_t)((k0) + 32 + sr) * LDQ + sc]); } while (0)
; #define SWRITE(b, i) do { *(bf16x8*)((char*)V_lds + (b) * SHM_V + vst0) = sr_[i].vs0;          \
;     *(bf16x8*)((char*)V_lds + (b) * SHM_V + vst1) = sr_[i].vs1; int kc = sc * 2;               \
;     *(bf16x8*)((char*)K_lds + (b) * SHM_K + KSWZ(sr, kc)) = sr_[i].ks0;                       \
;     *(bf16x8*)((char*)K_lds + (b) * SHM_K + KSWZ(32 + sr, kc)) = sr_[i].ks1; } while (0)
; template <bool SAFE>
; __device__ __forceinline__ void diff_core(const bf16* __restrict__ Kh, const bf16* __restrict__ Vh, const int NT, const bf16x8* qr, char* lds,
;                                           const int wid, const int lane_unused, f32x16* o, f32x16& lacc, float& l_reg) {
;     ...
;   const int kw0 = KSWZ(sr, sc * 2), kw1 = KSWZ(32 + sr, sc * 2);
;   SLOAD(0, 0); asm volatile("s_waitcnt vmcnt(0)" ::: "memory"); SWRITE(0, 0);
;   SLOAD(0, 64); asm volatile("s_waitcnt vmcnt(0)" ::: "memory"); SWRITE(1, 0); __syncthreads();
;   SLOAD(0, 128);
;   FIXUP(K_lds, true);
;   int bc = 1, bp = 0, bn = 2;
.LBB0_104:
	s_or_b64 exec, exec, s[4:5]
	v_and_b32_e32 v200, 63, v0
	v_lshlrev_b32_e32 v0, 4, v2
	v_and_b32_e32 v0, 0xc0, v0
	v_and_or_b32 v0, v1, 24, v0
	v_and_b32_e32 v2, 32, v4
	v_and_b32_e32 v1, 0x100, v1
	s_waitcnt lgkmcnt(0)
	v_add_u32_e32 v9, s62, v3
	v_or3_b32 v8, v0, v2, v1
	ds_read_b128 v[0:3], v9 offset:192
	ds_read_b128 v[4:7], v9 offset:224
	ds_read_b128 v[50:53], v9 offset:128
	ds_read_b128 v[54:57], v9 offset:160
	v_sub_f32_e32 v16, v16, v48
	v_sub_f32_e32 v17, v17, v48
	v_sub_f32_e32 v18, v18, v48
	v_sub_f32_e32 v19, v19, v48
	v_sub_f32_e32 v20, v20, v48
	v_sub_f32_e32 v21, v21, v48
	v_sub_f32_e32 v22, v22, v48
	v_sub_f32_e32 v23, v23, v48
	v_sub_f32_e32 v24, v24, v48
	v_sub_f32_e32 v25, v25, v48
	v_sub_f32_e32 v26, v26, v48
	v_sub_f32_e32 v27, v27, v48
	v_sub_f32_e32 v28, v28, v48
	v_sub_f32_e32 v29, v29, v48
	v_sub_f32_e32 v30, v30, v48
	v_sub_f32_e32 v31, v31, v48
	v_sub_f32_e32 v32, v32, v48
	v_sub_f32_e32 v33, v33, v48
	v_sub_f32_e32 v34, v34, v48
	v_sub_f32_e32 v35, v35, v48
	v_sub_f32_e32 v36, v36, v48
	v_sub_f32_e32 v37, v37, v48
	v_sub_f32_e32 v38, v38, v48
	v_sub_f32_e32 v39, v39, v48
	v_sub_f32_e32 v40, v40, v48
	v_sub_f32_e32 v41, v41, v48
	v_sub_f32_e32 v42, v42, v48
	v_sub_f32_e32 v43, v43, v48
	v_sub_f32_e32 v44, v44, v48
	v_sub_f32_e32 v45, v45, v48
	v_sub_f32_e32 v46, v46, v48
	v_sub_f32_e32 v47, v47, v48
	v_exp_f32_e32 v16, v16
	v_exp_f32_e32 v17, v17
	v_exp_f32_e32 v18, v18
	v_exp_f32_e32 v19, v19
	v_exp_f32_e32 v20, v20
	v_exp_f32_e32 v21, v21
	v_exp_f32_e32 v22, v22
	v_exp_f32_e32 v23, v23
	v_exp_f32_e32 v24, v24
	v_exp_f32_e32 v25, v25
	v_exp_f32_e32 v26, v26
	v_exp_f32_e32 v27, v27
	v_exp_f32_e32 v28, v28
	v_exp_f32_e32 v29, v29
	v_exp_f32_e32 v30, v30
	v_exp_f32_e32 v31, v31
	v_exp_f32_e32 v32, v32
	v_exp_f32_e32 v33, v33
	v_exp_f32_e32 v34, v34
	v_exp_f32_e32 v35, v35
	v_exp_f32_e32 v36, v36
	v_exp_f32_e32 v37, v37
	v_exp_f32_e32 v38, v38
	v_exp_f32_e32 v39, v39
	v_exp_f32_e32 v40, v40
	v_exp_f32_e32 v41, v41
	v_exp_f32_e32 v42, v42
	v_exp_f32_e32 v43, v43
	v_exp_f32_e32 v44, v44
	v_exp_f32_e32 v45, v45
	v_exp_f32_e32 v46, v46
	v_exp_f32_e32 v47, v47
	s_lshl_b32 s12, s8, 7
	s_cmp_lg_u32 0, -1
	s_cselect_b32 s5, 0, 0
	s_waitcnt lgkmcnt(2)
	v_pk_mul_f32 v[14:15], v[6:7], 0 op_sel_hi:[1,0]
	v_xor_b32_e32 v80, 0x80000000, v48
	v_add_u32_e32 v211, s5, v8
	v_pk_mul_f32 v[10:11], v[2:3], 0 op_sel_hi:[1,0]
	s_waitcnt lgkmcnt(0)
	v_pk_mul_f32 v[6:7], v[56:57], 0 op_sel_hi:[1,0]
	v_pk_mul_f32 v[2:3], v[52:53], 0 op_sel_hi:[1,0]
	v_pk_mul_f32 v[12:13], v[4:5], 0 op_sel_hi:[1,0]
	v_pk_mul_f32 v[8:9], v[0:1], 0 op_sel_hi:[1,0]
	v_pk_mul_f32 v[4:5], v[54:55], 0 op_sel_hi:[1,0]
	v_pk_mul_f32 v[0:1], v[50:51], 0 op_sel_hi:[1,0]
	v_cvt_pk_bf16_f32 v160, v16, v17
	v_cvt_pk_bf16_f32 v161, v18, v19
	v_cvt_pk_bf16_f32 v182, v20, v21
	v_cvt_pk_bf16_f32 v183, v22, v23
	v_cvt_pk_bf16_f32 v170, v24, v25
	v_cvt_pk_bf16_f32 v171, v26, v27
	v_cvt_pk_bf16_f32 v186, v28, v29
	v_cvt_pk_bf16_f32 v187, v30, v31
	v_cvt_pk_bf16_f32 v180, v32, v33
	v_cvt_pk_bf16_f32 v181, v34, v35
	v_cvt_pk_bf16_f32 v178, v36, v37
	v_cvt_pk_bf16_f32 v179, v38, v39
	v_cvt_pk_bf16_f32 v188, v40, v41
	v_cvt_pk_bf16_f32 v189, v42, v43
	v_cvt_pk_bf16_f32 v174, v44, v45
	v_cvt_pk_bf16_f32 v175, v46, v47
	v_mov_b32_e32 v64, 0
	v_mov_b64_e32 v[46:47], v[14:15]
	v_mov_b64_e32 v[62:63], v[14:15]
	v_mov_b64_e32 v[30:31], v[14:15]
	v_mov_b32_e32 v81, v80
	v_mov_b32_e32 v82, v80
	v_mov_b32_e32 v83, v80
	v_mov_b32_e32 v84, v80
	v_mov_b32_e32 v85, v80
	v_mov_b32_e32 v86, v80
	v_mov_b32_e32 v87, v80
	v_mov_b32_e32 v88, v80
	v_mov_b32_e32 v89, v80
	v_mov_b32_e32 v90, v80
	v_mov_b32_e32 v91, v80
	v_mov_b32_e32 v92, v80
	v_mov_b32_e32 v93, v80
	v_mov_b32_e32 v94, v80
	v_mov_b32_e32 v95, v80
	s_mov_b32 s4, 0
	s_mov_b32 s5, 1
	v_lshl_add_u64 v[190:191], s[10:11], 0, v[194:195]
	v_mad_u32_u24 v247, v201, s80, v194
	s_add_i32 s93, s92, -1
	s_mov_b32 s9, 2
	v_mov_b64_e32 v[44:45], v[12:13]
	v_mov_b64_e32 v[42:43], v[10:11]
	v_mov_b64_e32 v[40:41], v[8:9]
	v_mov_b64_e32 v[38:39], v[6:7]
	v_mov_b64_e32 v[36:37], v[4:5]
	v_mov_b64_e32 v[34:35], v[2:3]
	v_mov_b64_e32 v[32:33], v[0:1]
	v_mov_b64_e32 v[60:61], v[12:13]
	v_mov_b64_e32 v[58:59], v[10:11]
	v_mov_b64_e32 v[56:57], v[8:9]
	v_mov_b64_e32 v[54:55], v[6:7]
	v_mov_b64_e32 v[52:53], v[4:5]
	v_mov_b64_e32 v[50:51], v[2:3]
	v_mov_b64_e32 v[48:49], v[0:1]
	v_mov_b64_e32 v[28:29], v[12:13]
	v_mov_b64_e32 v[26:27], v[10:11]
	v_mov_b64_e32 v[24:25], v[8:9]
	v_mov_b64_e32 v[22:23], v[6:7]
	v_mov_b64_e32 v[20:21], v[4:5]
	v_mov_b64_e32 v[18:19], v[2:3]
	v_mov_b64_e32 v[16:17], v[0:1]
	s_mov_b32 s6, 1
	v_mov_b32_e32 v65, v64
	v_mov_b32_e32 v66, v64
	v_mov_b32_e32 v67, v64
	v_mov_b32_e32 v68, v64
	v_mov_b32_e32 v69, v64
	v_mov_b32_e32 v70, v64
	v_mov_b32_e32 v71, v64
	v_mov_b32_e32 v72, v64
	v_mov_b32_e32 v73, v64
	v_mov_b32_e32 v74, v64
	v_mov_b32_e32 v75, v64
	v_mov_b32_e32 v76, v64
	v_mov_b32_e32 v77, v64
	v_mov_b32_e32 v78, v64
	v_mov_b32_e32 v79, v64
	s_lshl_b32 s98, s6, 14
	v_add_u32_e32 v76, s98, v207
	v_add_u32_e32 v77, s98, v208
	ds_read_b128 v[68:71], v76 offset:49152
	ds_read_b128 v[72:75], v76 offset:57344
	s_waitcnt lgkmcnt(0)
; template <int KS, bool SAFE> __device__ __forceinline__ void fused_ks(f32x16* o, f32x16& lacc, int vb, const VFrag& cur, VFrag& nxt, f32x16& p0, f32x16& p1, float& ps, ...
;   if constexpr (KS < 3) { vfrag_issue<KS + 1>(nxt, vb); asm volatile("s_waitcnt lgkmcnt(8)" ::: "memory"); }
;   else asm volatile("s_waitcnt lgkmcnt(0)" ::: "memory");
;   const bf16x8 pa = (KS == 0) ? pa0 : (KS == 1) ? pa1 : (KS == 2) ? pa2 : pa3;
;   SBAR();
;   o[0] = MFMA32(pa, PKV(cur.l0, cur.h0), o[0]); SBAR(); sm1_chunk<KS * 4 + 0>(p0, p1); if constexpr (KS > 0) SM2_UNIT(2 * KS - 1); SBAR();
;   o[1] = MFMA32(pa, PKV(cur.l1, cur.h1), o[1]); SBAR(); sm1_chunk<KS * 4 + 1>(p0, p1);
;   if (dow) {
;     if constexpr (KS == 0) { asm volatile("s_waitcnt vmcnt(0)" ::: "memory"); *reinterpret_cast<bf16x8*>(sd.k0) = st.ks0; }
;     else if constexpr (KS == 1) *reinterpret_cast<bf16x8*>(sd.k1) = st.ks1;
;     else if constexpr (KS == 2) *reinterpret_cast<bf16x8*>(sd.v0) = st.vs0;
;     else *reinterpret_cast<bf16x8*>(sd.v1) = st.vs1;
;   }
;   SBAR();
;   o[2] = MFMA32(pa, PKV(cur.l2, cur.h2), o[2]); SBAR(); sm1_chunk<KS * 4 + 2>(p0, p1); SM2_UNIT(2 * KS); SBAR();
;   o[3] = MFMA32(pa, PKV(cur.l3, cur.h3), o[3]); SBAR(); sm1_chunk<KS * 4 + 3>(p0, p1); SBAR();
;   if constexpr (!SAFE) { lacc = MFMA32(pa, ones, lacc); SBAR(); }
; }
; template <bool SAFE> ...
;   bf16x8 kb[8];
; #pragma unroll
;   for (int d0 = 0; d0 < 4; ++d0) { const int cb = (cb0 + d0 * 16 + hi * 8) * 2;
;     kb[2 * d0] = *reinterpret_cast<const bf16x8*>((const char*)Ks + KSWZ(r32, cb));
;     kb[2 * d0 + 1] = *reinterpret_cast<const bf16x8*>((const char*)Ks + KSWZ(32 + r32, cb)); }
;   VFrag fa, fb;
;   vfrag_issue<0>(fa, vb);
;   p0 = MFMA32(kb[0], qr[0], cinit); p1 = MFMA32(kb[1], qr[0], cinit);
; #pragma unroll
;   for (int d0 = 1; d0 < 4; ++d0) { p0 = MFMA32(kb[2 * d0], qr[d0], p0); p1 = MFMA32(kb[2 * d0 + 1], qr[d0], p1); }
;   SBAR();
;   unsigned a0, a1, b0, b1; ps = 0.f;
;   fused_ks<0, SAFE>(o, lacc, vb, fa, fb, p0, p1, ps, a0, a1, b0, b1, pa0, pa1, pa2, pa3, st, sd, dow, ones);
;   fused_ks<1, SAFE>(o, lacc, vb, fb, fa, p0, p1, ps, a0, a1, b0, b1, pa0, pa1, pa2, pa3, st, sd, dow, ones);
;   fused_ks<2, SAFE>(o, lacc, vb, fa, fb, p0, p1, ps, a0, a1, b0, b1, pa0, pa1, pa2, pa3, st, sd, dow, ones);
;   fused_ks<3, SAFE>(o, lacc, vb, fb, fa, p0, p1, ps, a0, a1, b0, b1, pa0, pa1, pa2, pa3, st, sd, dow, ones);
.LBB0_105:
	ds_read_b128 v[212:215], v77 offset:49152
	ds_read_b128 v[216:219], v77 offset:57344
	s_lshl_b32 s7, s6, 14
	s_add_i32 s66, s7, 0
	s_add_i32 s98, s5, 2
	s_min_i32 s98, s98, s93
	s_mul_i32 s98, s98, 0x60000
	s_add_u32 s98, s10, s98
	s_addc_u32 s99, s11, 0
	s_add_u32 s100, s98, 0x30000
	s_addc_u32 s101, s99, 0
	v_add_u32_e32 v173, s66, v209
	v_mov_b32_e32 v176, v180
	v_mfma_f32_32x32x16_bf16 v[112:127], v[68:71], v[132:135], v[80:95]
	v_mov_b32_e32 v180, v160
	v_add_u32_e32 v160, s66, v210
	v_lshl_add_u32 v194, s4, 14, v211
	s_mov_b32 s8, s9
	s_lshl_b32 s9, s9, 14
	s_add_i32 s9, s9, 0
	v_add_u32_e32 v76, s9, v207
	v_mov_b32_e32 v184, v170
	v_mfma_f32_32x32x16_bf16 v[96:111], v[72:75], v[132:135], v[80:95]
	ds_read_b128 v[68:71], v173 offset:49152
	ds_read_b128 v[72:75], v173 offset:57344
	v_mov_b32_e32 v177, v181
	v_mov_b32_e32 v172, v188
	v_mov_b32_e32 v181, v161
	v_add_u32_e32 v188, s9, v205
	v_add_u32_e32 v161, s9, v203
	v_add_u32_e32 v170, s9, v204
	s_waitcnt lgkmcnt(3)
	v_mfma_f32_32x32x16_bf16 v[112:127], v[212:215], v[136:139], v[112:127]
	ds_read_b128 v[212:215], v160 offset:49152
	v_mov_b32_e32 v185, v171
	s_waitcnt lgkmcnt(3)
	v_mfma_f32_32x32x16_bf16 v[96:111], v[216:219], v[136:139], v[96:111]
	ds_read_b128 v[216:219], v160 offset:57344
	v_mov_b32_e32 v173, v189
	v_add_u32_e32 v189, s9, v206
	v_add_u32_e32 v77, s9, v208
	s_waitcnt lgkmcnt(3)
	v_mfma_f32_32x32x16_bf16 v[112:127], v[68:71], v[140:143], v[112:127]
	ds_read_b64_tr_b16 v[220:221], v194 offset:0
	ds_read_b64_tr_b16 v[222:223], v194 offset:0x800
	s_waitcnt lgkmcnt(4)
	v_mfma_f32_32x32x16_bf16 v[96:111], v[72:75], v[140:143], v[96:111]
	s_waitcnt lgkmcnt(3)
	v_mfma_f32_32x32x16_bf16 v[112:127], v[212:215], v[144:147], v[112:127]
	ds_read_b64_tr_b16 v[212:213], v194 offset:0x200
	ds_read_b64_tr_b16 v[214:215], v194 offset:0xa00
	ds_read_b64_tr_b16 v[224:225], v194 offset:0x400
	ds_read_b64_tr_b16 v[226:227], v194 offset:0xc00
	ds_read_b64_tr_b16 v[228:229], v194 offset:0x600
	ds_read_b64_tr_b16 v[230:231], v194 offset:0xe00
	s_waitcnt lgkmcnt(7)
	v_mfma_f32_32x32x16_bf16 v[96:111], v[216:219], v[144:147], v[96:111]
	ds_read_b64_tr_b16 v[216:217], v194 offset:0x1000
	ds_read_b64_tr_b16 v[218:219], v194 offset:0x1800
	ds_read_b64_tr_b16 v[232:233], v194 offset:0x1200
	ds_read_b64_tr_b16 v[234:235], v194 offset:0x1a00
	ds_read_b64_tr_b16 v[236:237], v194 offset:0x1400
	ds_read_b64_tr_b16 v[238:239], v194 offset:0x1c00
	ds_read_b64_tr_b16 v[240:241], v194 offset:0x1600
	ds_read_b64_tr_b16 v[242:243], v194 offset:0x1e00
	s_waitcnt lgkmcnt(8)
	v_mfma_f32_32x32x16_bf16 v[48:63], v[180:183], v[220:223], v[48:63]
	s_nop 0
	v_exp_f32_e32 v112, v112
	v_exp_f32_e32 v113, v113
	v_mfma_f32_32x32x16_bf16 v[32:47], v[180:183], v[212:215], v[32:47]
	v_exp_f32_e32 v114, v114
	v_exp_f32_e32 v115, v115
	s_waitcnt vmcnt(3)
	ds_write_b128 v161, v[166:169] offset:49152
	global_load_dwordx4 v[166:169], v247, s[98:99] offset:1024
	v_mfma_f32_32x32x16_bf16 v[0:15], v[180:183], v[224:227], v[0:15]
	v_exp_f32_e32 v171, v116
	v_cvt_pk_bf16_f32 v160, v112, v113
	v_cvt_pk_bf16_f32 v161, v114, v115
	v_exp_f32_e32 v220, v117
	v_mfma_f32_32x32x16_bf16 v[16:31], v[180:183], v[228:231], v[16:31]
	v_exp_f32_e32 v221, v118
	v_exp_f32_e32 v222, v119
	v_mfma_f32_16x16x32_bf16 v[64:67], v[180:183], v[148:151], v[64:67]
	ds_read_b64_tr_b16 v[112:113], v194 offset:0x2000
	ds_read_b64_tr_b16 v[114:115], v194 offset:0x2800
	ds_read_b64_tr_b16 v[116:117], v194 offset:0x2200
	ds_read_b64_tr_b16 v[118:119], v194 offset:0x2a00
	ds_read_b64_tr_b16 v[248:249], v194 offset:0x2400
	ds_read_b64_tr_b16 v[250:251], v194 offset:0x2c00
	ds_read_b64_tr_b16 v[212:213], v194 offset:0x2600
	ds_read_b64_tr_b16 v[214:215], v194 offset:0x2e00
	s_waitcnt lgkmcnt(8)
	v_mfma_f32_32x32x16_bf16 v[48:63], v[184:187], v[216:219], v[48:63]
	v_cvt_pk_bf16_f32 v182, v171, v220
	v_cvt_pk_bf16_f32 v183, v221, v222
	v_exp_f32_e32 v120, v120
	v_exp_f32_e32 v121, v121
	v_mfma_f32_32x32x16_bf16 v[32:47], v[184:187], v[232:235], v[32:47]
	v_exp_f32_e32 v122, v122
	v_exp_f32_e32 v123, v123
	s_waitcnt vmcnt(3)
	ds_write_b128 v170, v[162:165] offset:49152
	global_load_dwordx4 v[162:165], v247, s[100:101] offset:1024
	v_mfma_f32_32x32x16_bf16 v[0:15], v[184:187], v[236:239], v[0:15]
	v_exp_f32_e32 v180, v124
	v_exp_f32_e32 v181, v125
	v_cvt_pk_bf16_f32 v170, v120, v121
	v_cvt_pk_bf16_f32 v171, v122, v123
	v_mfma_f32_32x32x16_bf16 v[16:31], v[184:187], v[240:243], v[16:31]
	v_exp_f32_e32 v220, v126
	v_exp_f32_e32 v221, v127
	v_mfma_f32_16x16x32_bf16 v[64:67], v[184:187], v[148:151], v[64:67]
	s_waitcnt lgkmcnt(0)
	s_barrier
; #define SBAR() __builtin_amdgcn_sched_barrier(0)
; template <int KS, bool SAFE> __device__ __forceinline__ void fused_ks(f32x16* o, f32x16& lacc, int vb, const VFrag& cur, VFrag& nxt, f32x16& p0, f32x16& p1, float& ps, ...
;   if constexpr (KS < 3) { vfrag_issue<KS + 1>(nxt, vb); asm volatile("s_waitcnt lgkmcnt(8)" ::: "memory"); }
;   else asm volatile("s_waitcnt lgkmcnt(0)" ::: "memory");
;   const bf16x8 pa = (KS == 0) ? pa0 : (KS == 1) ? pa1 : (KS == 2) ? pa2 : pa3;
;   SBAR();
;   o[0] = MFMA32(pa, PKV(cur.l0, cur.h0), o[0]); SBAR(); sm1_chunk<KS * 4 + 0>(p0, p1); if constexpr (KS > 0) SM2_UNIT(2 * KS - 1); SBAR();
;   o[1] = MFMA32(pa, PKV(cur.l1, cur.h1), o[1]); SBAR(); sm1_chunk<KS * 4 + 1>(p0, p1);
;   if (dow) {
;     if constexpr (KS == 0) { asm volatile("s_waitcnt vmcnt(0)" ::: "memory"); *reinterpret_cast<bf16x8*>(sd.k0) = st.ks0; }
;     else if constexpr (KS == 1) *reinterpret_cast<bf16x8*>(sd.k1) = st.ks1;
;     else if constexpr (KS == 2) *reinterpret_cast<bf16x8*>(sd.v0) = st.vs0;
;     else *reinterpret_cast<bf16x8*>(sd.v1) = st.vs1;
;   }
;   SBAR();
;   o[2] = MFMA32(pa, PKV(cur.l2, cur.h2), o[2]); SBAR(); sm1_chunk<KS * 4 + 2>(p0, p1); SM2_UNIT(2 * KS); SBAR();
;   o[3] = MFMA32(pa, PKV(cur.l3, cur.h3), o[3]); SBAR(); sm1_chunk<KS * 4 + 3>(p0, p1); SBAR();
;   if constexpr (!SAFE) { lacc = MFMA32(pa, ones, lacc); SBAR(); }
; }
; template <bool SAFE>
; __device__ __forceinline__ void diff_core(const bf16* __restrict__ Kh, const bf16* __restrict__ Vh, const int NT, const bf16x8* qr, char* lds,
;                                           const int wid, const int lane_unused, f32x16* o, f32x16& lacc, float& l_reg) {
;     ...
;   for (int j = 1; j < NT; ++j) {
;     const bool dow = true;
;     const bf16* Kc = (const bf16*)((const char*)K_lds + bc * SHM_K);
;     StgDst sd;
;     sd.v0 = (char*)V_lds + bn * SHM_V + vst0; sd.v1 = (char*)V_lds + bn * SHM_V + vst1;
;     sd.k0 = (char*)K_lds + bn * SHM_K + kw0;  sd.k1 = (char*)K_lds + bn * SHM_K + kw1;
;     tile_step<SAFE>(o, lacc, Kc, vb0 + bp * SHM_V, qr, rk, hi, cb0, p0, p1, cinit, ps, pa0, pa1, pa2, pa3, sr_[0], sd, dow, ones);
;     SLOAD(0, min(j + 2, NT - 1) * 64);
;     SBAR();
;     if constexpr (SAFE) FIXUP(Kc, false);
;     asm volatile("s_waitcnt lgkmcnt(0)" ::: "memory"); __builtin_amdgcn_s_barrier(); asm volatile("" ::: "memory");
;     const int t_ = bp; bp = bc; bc = bn; bn = t_;
	ds_read_b128 v[68:71], v76 offset:49152
	ds_read_b128 v[72:75], v76 offset:57344
	ds_read_b64_tr_b16 v[120:121], v194 offset:0x3000
	ds_read_b64_tr_b16 v[122:123], v194 offset:0x3800
	ds_read_b64_tr_b16 v[124:125], v194 offset:0x3200
	ds_read_b64_tr_b16 v[126:127], v194 offset:0x3a00
	ds_read_b64_tr_b16 v[252:253], v194 offset:0x3400
	ds_read_b64_tr_b16 v[254:255], v194 offset:0x3c00
	ds_read_b64_tr_b16 v[216:217], v194 offset:0x3600
	ds_read_b64_tr_b16 v[218:219], v194 offset:0x3e00
	v_mfma_f32_32x32x16_bf16 v[48:63], v[176:179], v[112:115], v[48:63]
	v_cvt_pk_bf16_f32 v186, v180, v181
	v_cvt_pk_bf16_f32 v187, v220, v221
	v_exp_f32_e32 v96, v96
	v_exp_f32_e32 v97, v97
	v_mfma_f32_32x32x16_bf16 v[32:47], v[176:179], v[116:119], v[32:47]
	v_exp_f32_e32 v98, v98
	v_exp_f32_e32 v99, v99
	s_waitcnt vmcnt(3)
	ds_write_b128 v188, v[156:159]
	global_load_dwordx4 v[156:159], v247, s[98:99] offset:2048
	v_mfma_f32_32x32x16_bf16 v[0:15], v[176:179], v[248:251], v[0:15]
	v_cvt_pk_bf16_f32 v180, v96, v97
	v_cvt_pk_bf16_f32 v181, v98, v99
	v_exp_f32_e32 v100, v100
	v_exp_f32_e32 v101, v101
	v_mfma_f32_32x32x16_bf16 v[16:31], v[176:179], v[212:215], v[16:31]
	v_exp_f32_e32 v96, v102
	v_exp_f32_e32 v97, v103
	v_mfma_f32_16x16x32_bf16 v[64:67], v[176:179], v[148:151], v[64:67]
	s_waitcnt lgkmcnt(0)
	v_mfma_f32_32x32x16_bf16 v[48:63], v[172:175], v[120:123], v[48:63]
	v_cvt_pk_bf16_f32 v178, v100, v101
	v_cvt_pk_bf16_f32 v179, v96, v97
	v_exp_f32_e32 v98, v104
	v_exp_f32_e32 v99, v105
	v_mfma_f32_32x32x16_bf16 v[32:47], v[172:175], v[124:127], v[32:47]
	v_exp_f32_e32 v96, v106
	v_exp_f32_e32 v97, v107
	s_waitcnt vmcnt(3)
	ds_write_b128 v189, v[152:155]
	global_load_dwordx4 v[152:155], v247, s[100:101] offset:2048
	v_mfma_f32_32x32x16_bf16 v[0:15], v[172:175], v[252:255], v[0:15]
	v_cvt_pk_bf16_f32 v188, v98, v99
	v_cvt_pk_bf16_f32 v189, v96, v97
	v_exp_f32_e32 v100, v108
	v_exp_f32_e32 v101, v109
	v_mfma_f32_32x32x16_bf16 v[16:31], v[172:175], v[216:219], v[16:31]
	v_exp_f32_e32 v96, v110
	v_exp_f32_e32 v97, v111
	v_mfma_f32_16x16x32_bf16 v[64:67], v[172:175], v[148:151], v[64:67]
	v_cvt_pk_bf16_f32 v174, v100, v101
	v_cvt_pk_bf16_f32 v175, v96, v97
	s_add_i32 s5, s5, 1
	s_mov_b32 s9, s4
	s_mov_b32 s4, s6
	s_cmp_lg_u32 s92, s5
	s_mov_b32 s6, s8
	s_cbranch_scc1 .LBB0_105
; #define MFMA32(a, b, c) __builtin_amdgcn_mfma_f32_32x32x16_bf16(a, b, c, 0, 0, 0)
; template <bool SAFE>
; __device__ __forceinline__ void diff_core(const bf16* __restrict__ Kh, const bf16* __restrict__ Vh, const int NT, const bf16x8* qr, char* lds,
;                                           const int wid, const int lane_unused, f32x16* o, f32x16& lacc, float& l_reg) {
;     ...
;   pv_d0(o, vb0 + bp * SHM_V, pa0, pa1, pa2, pa3);
;   if constexpr (!SAFE) {
;     lacc = MFMA32(pa0, ones, lacc); lacc = MFMA32(pa1, ones, lacc); lacc = MFMA32(pa2, ones, lacc); lacc = MFMA32(pa3, ones, lacc); }
; __device__ __forceinline__ void diff_attn_item(const bf16* __restrict__ qkv, bf16* __restrict__ mix, const float* __restrict__ dg,
;                                int tok0  , int key0  , int seq, int head, float lam, float oscale, const int W) {
;     ...
;     bool bad = (FORCE_SAFE != 0);
; #pragma unroll
;     for (int r = 0; r < 16; ++r) bad = bad || !(lacc[r] < 1.0e30f);
;     if (lane == 0) flag_l[wid] = __any(bad) ? 1 : 0;
	s_waitcnt vmcnt(0)
	v_add_u32_e32 v168, s7, v211
	ds_read_b64_tr_b16 v[80:81], v168 offset:0
	ds_read_b64_tr_b16 v[82:83], v168 offset:0x800
	ds_read_b64_tr_b16 v[84:85], v168 offset:0x1000
	ds_read_b64_tr_b16 v[86:87], v168 offset:0x1800
	ds_read_b64_tr_b16 v[88:89], v168 offset:0x2000
	ds_read_b64_tr_b16 v[90:91], v168 offset:0x2800
	ds_read_b64_tr_b16 v[92:93], v168 offset:0x3000
	ds_read_b64_tr_b16 v[94:95], v168 offset:0x3800
	s_waitcnt lgkmcnt(0)
	s_waitcnt vmcnt(0)
	v_mov_b32_e32 v162, v182
	v_mov_b32_e32 v163, v183
	v_mov_b32_e32 v172, v186
	v_mov_b32_e32 v173, v187
	v_mov_b32_e32 v182, v178
	v_mov_b32_e32 v183, v179
	v_mov_b32_e32 v190, v174
	v_mov_b32_e32 v191, v175
	ds_read_b64_tr_b16 v[96:97], v168 offset:0x200
	ds_read_b64_tr_b16 v[98:99], v168 offset:0xa00
	ds_read_b64_tr_b16 v[100:101], v168 offset:0x1200
	ds_read_b64_tr_b16 v[102:103], v168 offset:0x1a00
	ds_read_b64_tr_b16 v[104:105], v168 offset:0x2200
	ds_read_b64_tr_b16 v[106:107], v168 offset:0x2a00
	ds_read_b64_tr_b16 v[108:109], v168 offset:0x3200
	ds_read_b64_tr_b16 v[110:111], v168 offset:0x3a00
	s_waitcnt lgkmcnt(0)
	ds_read_b64_tr_b16 v[112:113], v168 offset:0x400
	ds_read_b64_tr_b16 v[114:115], v168 offset:0xc00
	ds_read_b64_tr_b16 v[116:117], v168 offset:0x1400
	ds_read_b64_tr_b16 v[118:119], v168 offset:0x1c00
	ds_read_b64_tr_b16 v[120:121], v168 offset:0x2400
	ds_read_b64_tr_b16 v[122:123], v168 offset:0x2c00
	ds_read_b64_tr_b16 v[124:125], v168 offset:0x3400
	ds_read_b64_tr_b16 v[126:127], v168 offset:0x3c00
	s_waitcnt lgkmcnt(0)
	ds_read_b64_tr_b16 v[152:153], v168 offset:0x600
	ds_read_b64_tr_b16 v[154:155], v168 offset:0xe00
	ds_read_b64_tr_b16 v[156:157], v168 offset:0x1600
	ds_read_b64_tr_b16 v[158:159], v168 offset:0x1e00
	ds_read_b64_tr_b16 v[164:165], v168 offset:0x2600
	ds_read_b64_tr_b16 v[166:167], v168 offset:0x2e00
	ds_read_b64_tr_b16 v[174:175], v168 offset:0x3600
	ds_read_b64_tr_b16 v[176:177], v168 offset:0x3e00
	s_waitcnt lgkmcnt(0)
	v_mfma_f32_16x16x32_bf16 v[64:67], v[160:163], v[148:151], v[64:67]
	v_cmp_eq_u32_e32 vcc, 0, v200
	v_mfma_f32_32x32x16_bf16 v[48:63], v[160:163], v[80:83], v[48:63]
	v_mfma_f32_32x32x16_bf16 v[32:47], v[160:163], v[96:99], v[32:47]
	v_mfma_f32_32x32x16_bf16 v[0:15], v[160:163], v[112:115], v[0:15]
	v_mfma_f32_32x32x16_bf16 v[16:31], v[160:163], v[152:155], v[16:31]
	v_mfma_f32_16x16x32_bf16 v[64:67], v[170:173], v[148:151], v[64:67]
	v_mfma_f32_32x32x16_bf16 v[48:63], v[170:173], v[84:87], v[48:63]
	v_mfma_f32_32x32x16_bf16 v[32:47], v[170:173], v[100:103], v[32:47]
	v_mfma_f32_32x32x16_bf16 v[0:15], v[170:173], v[116:119], v[0:15]
	v_mfma_f32_32x32x16_bf16 v[16:31], v[170:173], v[156:159], v[16:31]
	v_mfma_f32_16x16x32_bf16 v[64:67], v[180:183], v[148:151], v[64:67]
	v_mfma_f32_32x32x16_bf16 v[48:63], v[180:183], v[88:91], v[48:63]
	v_mfma_f32_32x32x16_bf16 v[32:47], v[180:183], v[104:107], v[32:47]
	v_mfma_f32_32x32x16_bf16 v[0:15], v[180:183], v[120:123], v[0:15]
	v_mfma_f32_32x32x16_bf16 v[16:31], v[180:183], v[164:167], v[16:31]
	v_mfma_f32_16x16x32_bf16 v[64:67], v[188:191], v[148:151], v[64:67]
	v_mfma_f32_32x32x16_bf16 v[48:63], v[188:191], v[92:95], v[48:63]
	v_mfma_f32_32x32x16_bf16 v[32:47], v[188:191], v[108:111], v[32:47]
	v_mfma_f32_32x32x16_bf16 v[0:15], v[188:191], v[124:127], v[0:15]
	v_mfma_f32_32x32x16_bf16 v[16:31], v[188:191], v[174:177], v[16:31]
	v_and_b32_e32 v248, 15, v200
	v_lshrrev_b32_e32 v249, 4, v200
	v_and_b32_e32 v250, 1, v200
	v_lshlrev_b32_e32 v249, 4, v249
	v_lshl_add_u32 v249, v250, 6, v249
	v_add_u32_e32 v249, s62, v249
	v_cmp_gt_u32_e64 s[98:99], 2, v248
	v_lshl_add_u32 v250, v198, 4, s62
	s_nop 7
	s_and_saveexec_b64 s[100:101], s[98:99]
	ds_write_b128 v249, v[64:67]
	s_mov_b64 exec, s[100:101]
	s_waitcnt lgkmcnt(0)
	ds_read_b128 v[64:67], v250
	ds_read_b128 v[68:71], v250 offset:32
	ds_read_b128 v[72:75], v250 offset:64
	ds_read_b128 v[76:79], v250 offset:96
	s_waitcnt lgkmcnt(0)
	s_and_saveexec_b64 s[6:7], vcc
	s_cbranch_execz .LBB0_108
	s_nop 5
	v_cmp_ngt_f32_e32 vcc, s85, v64
	v_cmp_ngt_f32_e64 s[4:5], s85, v65
	s_or_b64 s[4:5], vcc, s[4:5]
	v_cmp_ngt_f32_e32 vcc, s85, v66
	s_or_b64 s[4:5], s[4:5], vcc
	v_cmp_ngt_f32_e32 vcc, s85, v67
	s_or_b64 s[4:5], s[4:5], vcc
	v_cmp_ngt_f32_e32 vcc, s85, v68
	s_or_b64 s[4:5], s[4:5], vcc
	v_cmp_ngt_f32_e32 vcc, s85, v69
	s_or_b64 s[4:5], s[4:5], vcc
	v_cmp_ngt_f32_e32 vcc, s85, v70
	s_or_b64 s[4:5], s[4:5], vcc
	v_cmp_ngt_f32_e32 vcc, s85, v71
	s_or_b64 s[4:5], s[4:5], vcc
	v_cmp_ngt_f32_e32 vcc, s85, v72
	s_or_b64 s[4:5], s[4:5], vcc
	v_cmp_ngt_f32_e32 vcc, s85, v73
	s_or_b64 s[4:5], s[4:5], vcc
	v_cmp_ngt_f32_e32 vcc, s85, v74
	s_or_b64 s[4:5], s[4:5], vcc
	v_cmp_ngt_f32_e32 vcc, s85, v75
	s_or_b64 s[4:5], s[4:5], vcc
	v_cmp_ngt_f32_e32 vcc, s85, v76
	s_or_b64 s[4:5], s[4:5], vcc
	v_cmp_ngt_f32_e32 vcc, s85, v77
	s_or_b64 s[4:5], s[4:5], vcc
	v_cmp_ngt_f32_e32 vcc, s85, v78
	s_or_b64 s[4:5], s[4:5], vcc
	v_cmp_ngt_f32_e32 vcc, s85, v79
	s_or_b64 s[4:5], s[4:5], vcc
	v_cndmask_b32_e64 v80, 0, 1, s[4:5]
	v_cmp_ne_u32_e32 vcc, 0, v80
	s_cmp_lg_u64 vcc, 0
	s_cselect_b64 s[4:5], -1, 0
	v_cndmask_b32_e64 v80, 0, 1, s[4:5]
	v_readlane_b32 s4, v246, 17
	s_nop 1
	v_mov_b32_e32 v81, s4
	ds_write_b32 v81, v80

; #define SLOAD(i, k0) do { sr_[i].vs0 = *reinterpret_cast<const bf16x8*>(&Vh[(size_t)((k0) + sr) * LDQ + sc]); sr_[i].vs1 = *reinterpret_cast<const bf16x8*>(&Vh[(size_t)((k0) + 32 + sr) * LDQ + sc]); \
;     sr_[i].ks0 = *reinterpret_cast<const bf16x8*>(&Kh[(size_t)((k0) + sr) * LDQ + sc]); sr_[i].ks1 = *reinterpret_cast<const bf16x8*>(&Kh[(size_t)((k0) + 32 + sr) * LDQ + sc]); } while (0)
; #define SWRITE(b, i) do { *(bf16x8*)((char*)V_lds + (b) * SHM_V + vst0) = sr_[i].vs0;          \
;     *(bf16x8*)((char*)V_lds + (b) * SHM_V + vst1) = sr_[i].vs1; int kc = sc * 2;               \
;     *(bf16x8*)((char*)K_lds + (b) * SHM_K + KSWZ(sr, kc)) = sr_[i].ks0;                       \
;     *(bf16x8*)((char*)K_lds + (b) * SHM_K + KSWZ(32 + sr, kc)) = sr_[i].ks1; } while (0)
; template <bool SAFE>
; __device__ __forceinline__ void diff_core(const bf16* __restrict__ Kh, const bf16* __restrict__ Vh, const int NT, const bf16x8* qr, char* lds,
;                                           const int wid, const int lane_unused, f32x16* o, f32x16& lacc, float& l_reg) {
;     ...
;   const int kw0 = KSWZ(sr, sc * 2), kw1 = KSWZ(32 + sr, sc * 2);
;   SLOAD(0, 0); asm volatile("s_waitcnt vmcnt(0)" ::: "memory"); SWRITE(0, 0);
;   SLOAD(0, 64); asm volatile("s_waitcnt vmcnt(0)" ::: "memory"); SWRITE(1, 0); __syncthreads();
;   SLOAD(0, 128);
;   FIXUP(K_lds, true);
;   int bc = 1, bp = 0, bn = 2;
.LBB0_315:
	s_or_b64 exec, exec, s[6:7]
	v_and_b32_e32 v200, 63, v0
	v_lshlrev_b32_e32 v0, 4, v2
	v_and_b32_e32 v0, 0xc0, v0
	v_and_or_b32 v0, v1, 24, v0
	v_and_b32_e32 v2, 32, v4
	v_and_b32_e32 v1, 0x100, v1
	s_waitcnt lgkmcnt(0)
	v_add_u32_e32 v9, s62, v3
	v_or3_b32 v8, v0, v2, v1
	ds_read_b128 v[0:3], v9 offset:192
	ds_read_b128 v[4:7], v9 offset:224
	ds_read_b128 v[50:53], v9 offset:128
	ds_read_b128 v[54:57], v9 offset:160
	v_sub_f32_e32 v16, v16, v48
	v_sub_f32_e32 v17, v17, v48
	v_sub_f32_e32 v18, v18, v48
	v_sub_f32_e32 v19, v19, v48
	v_sub_f32_e32 v20, v20, v48
	v_sub_f32_e32 v21, v21, v48
	v_sub_f32_e32 v22, v22, v48
	v_sub_f32_e32 v23, v23, v48
	v_sub_f32_e32 v24, v24, v48
	v_sub_f32_e32 v25, v25, v48
	v_sub_f32_e32 v26, v26, v48
	v_sub_f32_e32 v27, v27, v48
	v_sub_f32_e32 v28, v28, v48
	v_sub_f32_e32 v29, v29, v48
	v_sub_f32_e32 v30, v30, v48
	v_sub_f32_e32 v31, v31, v48
	v_sub_f32_e32 v32, v32, v48
	v_sub_f32_e32 v33, v33, v48
	v_sub_f32_e32 v34, v34, v48
	v_sub_f32_e32 v35, v35, v48
	v_sub_f32_e32 v36, v36, v48
	v_sub_f32_e32 v37, v37, v48
	v_sub_f32_e32 v38, v38, v48
	v_sub_f32_e32 v39, v39, v48
	v_sub_f32_e32 v40, v40, v48
	v_sub_f32_e32 v41, v41, v48
	v_sub_f32_e32 v42, v42, v48
	v_sub_f32_e32 v43, v43, v48
	v_sub_f32_e32 v44, v44, v48
	v_sub_f32_e32 v45, v45, v48
	v_sub_f32_e32 v46, v46, v48
	v_sub_f32_e32 v47, v47, v48
	v_exp_f32_e32 v16, v16
	v_exp_f32_e32 v17, v17
	v_exp_f32_e32 v18, v18
	v_exp_f32_e32 v19, v19
	v_exp_f32_e32 v20, v20
	v_exp_f32_e32 v21, v21
	v_exp_f32_e32 v22, v22
	v_exp_f32_e32 v23, v23
	v_exp_f32_e32 v24, v24
	v_exp_f32_e32 v25, v25
	v_exp_f32_e32 v26, v26
	v_exp_f32_e32 v27, v27
	v_exp_f32_e32 v28, v28
	v_exp_f32_e32 v29, v29
	v_exp_f32_e32 v30, v30
	v_exp_f32_e32 v31, v31
	v_exp_f32_e32 v32, v32
	v_exp_f32_e32 v33, v33
	v_exp_f32_e32 v34, v34
	v_exp_f32_e32 v35, v35
	v_exp_f32_e32 v36, v36
	v_exp_f32_e32 v37, v37
	v_exp_f32_e32 v38, v38
	v_exp_f32_e32 v39, v39
	v_exp_f32_e32 v40, v40
	v_exp_f32_e32 v41, v41
	v_exp_f32_e32 v42, v42
	v_exp_f32_e32 v43, v43
	v_exp_f32_e32 v44, v44
	v_exp_f32_e32 v45, v45
	v_exp_f32_e32 v46, v46
	v_exp_f32_e32 v47, v47
	s_lshl_b32 s20, s26, 7
	s_cmp_lg_u32 0, -1
	s_cselect_b32 s7, 0, 0
	s_waitcnt lgkmcnt(2)
	v_pk_mul_f32 v[14:15], v[6:7], 0 op_sel_hi:[1,0]
	v_xor_b32_e32 v80, 0x80000000, v48
	v_add_u32_e32 v211, s7, v8
	v_pk_mul_f32 v[10:11], v[2:3], 0 op_sel_hi:[1,0]
	s_waitcnt lgkmcnt(0)
	v_pk_mul_f32 v[6:7], v[56:57], 0 op_sel_hi:[1,0]
	v_pk_mul_f32 v[2:3], v[52:53], 0 op_sel_hi:[1,0]
	v_pk_mul_f32 v[12:13], v[4:5], 0 op_sel_hi:[1,0]
	v_pk_mul_f32 v[8:9], v[0:1], 0 op_sel_hi:[1,0]
	v_pk_mul_f32 v[4:5], v[54:55], 0 op_sel_hi:[1,0]
	v_pk_mul_f32 v[0:1], v[50:51], 0 op_sel_hi:[1,0]
	v_cvt_pk_bf16_f32 v160, v16, v17
	v_cvt_pk_bf16_f32 v161, v18, v19
	v_cvt_pk_bf16_f32 v182, v20, v21
	v_cvt_pk_bf16_f32 v183, v22, v23
	v_cvt_pk_bf16_f32 v170, v24, v25
	v_cvt_pk_bf16_f32 v171, v26, v27
	v_cvt_pk_bf16_f32 v186, v28, v29
	v_cvt_pk_bf16_f32 v187, v30, v31
	v_cvt_pk_bf16_f32 v180, v32, v33
	v_cvt_pk_bf16_f32 v181, v34, v35
	v_cvt_pk_bf16_f32 v178, v36, v37
	v_cvt_pk_bf16_f32 v179, v38, v39
	v_cvt_pk_bf16_f32 v188, v40, v41
	v_cvt_pk_bf16_f32 v189, v42, v43
	v_cvt_pk_bf16_f32 v174, v44, v45
	v_cvt_pk_bf16_f32 v175, v46, v47
	v_mov_b32_e32 v64, 0
	v_mov_b64_e32 v[46:47], v[14:15]
	v_mov_b64_e32 v[62:63], v[14:15]
	v_mov_b64_e32 v[30:31], v[14:15]
	v_mov_b32_e32 v81, v80
	v_mov_b32_e32 v82, v80
	v_mov_b32_e32 v83, v80
	v_mov_b32_e32 v84, v80
	v_mov_b32_e32 v85, v80
	v_mov_b32_e32 v86, v80
	v_mov_b32_e32 v87, v80
	v_mov_b32_e32 v88, v80
	v_mov_b32_e32 v89, v80
	v_mov_b32_e32 v90, v80
	v_mov_b32_e32 v91, v80
	v_mov_b32_e32 v92, v80
	v_mov_b32_e32 v93, v80
	v_mov_b32_e32 v94, v80
	v_mov_b32_e32 v95, v80
	s_mov_b32 s6, 0
	s_mov_b32 s7, 1
	v_lshl_add_u64 v[190:191], s[14:15], 0, v[194:195]
	v_mad_u32_u24 v247, v201, s41, v194
	s_add_i32 s64, s55, -1
	s_mov_b32 s27, 2
	v_mov_b64_e32 v[44:45], v[12:13]
	v_mov_b64_e32 v[42:43], v[10:11]
	v_mov_b64_e32 v[40:41], v[8:9]
	v_mov_b64_e32 v[38:39], v[6:7]
	v_mov_b64_e32 v[36:37], v[4:5]
	v_mov_b64_e32 v[34:35], v[2:3]
	v_mov_b64_e32 v[32:33], v[0:1]
	v_mov_b64_e32 v[60:61], v[12:13]
	v_mov_b64_e32 v[58:59], v[10:11]
	v_mov_b64_e32 v[56:57], v[8:9]
	v_mov_b64_e32 v[54:55], v[6:7]
	v_mov_b64_e32 v[52:53], v[4:5]
	v_mov_b64_e32 v[50:51], v[2:3]
	v_mov_b64_e32 v[48:49], v[0:1]
	v_mov_b64_e32 v[28:29], v[12:13]
	v_mov_b64_e32 v[26:27], v[10:11]
	v_mov_b64_e32 v[24:25], v[8:9]
	v_mov_b64_e32 v[22:23], v[6:7]
	v_mov_b64_e32 v[20:21], v[4:5]
	v_mov_b64_e32 v[18:19], v[2:3]
	v_mov_b64_e32 v[16:17], v[0:1]
	s_mov_b32 s10, 1
	v_mov_b32_e32 v65, v64
	v_mov_b32_e32 v66, v64
	v_mov_b32_e32 v67, v64
	v_mov_b32_e32 v68, v64
	v_mov_b32_e32 v69, v64
	v_mov_b32_e32 v70, v64
	v_mov_b32_e32 v71, v64
	v_mov_b32_e32 v72, v64
	v_mov_b32_e32 v73, v64
	v_mov_b32_e32 v74, v64
	v_mov_b32_e32 v75, v64
	v_mov_b32_e32 v76, v64
	v_mov_b32_e32 v77, v64
	v_mov_b32_e32 v78, v64
	v_mov_b32_e32 v79, v64
	s_lshl_b32 s98, s10, 14
	v_add_u32_e32 v76, s98, v207
	v_add_u32_e32 v77, s98, v208
	ds_read_b128 v[68:71], v76 offset:49152
	ds_read_b128 v[72:75], v76 offset:57344
	s_waitcnt lgkmcnt(0)
; template <int KS, bool SAFE> __device__ __forceinline__ void fused_ks(f32x16* o, f32x16& lacc, int vb, const VFrag& cur, VFrag& nxt, f32x16& p0, f32x16& p1, float& ps, ...
;   if constexpr (KS < 3) { vfrag_issue<KS + 1>(nxt, vb); asm volatile("s_waitcnt lgkmcnt(8)" ::: "memory"); }
;   else asm volatile("s_waitcnt lgkmcnt(0)" ::: "memory");
;   const bf16x8 pa = (KS == 0) ? pa0 : (KS == 1) ? pa1 : (KS == 2) ? pa2 : pa3;
;   SBAR();
;   o[0] = MFMA32(pa, PKV(cur.l0, cur.h0), o[0]); SBAR(); sm1_chunk<KS * 4 + 0>(p0, p1); if constexpr (KS > 0) SM2_UNIT(2 * KS - 1); SBAR();
;   o[1] = MFMA32(pa, PKV(cur.l1, cur.h1), o[1]); SBAR(); sm1_chunk<KS * 4 + 1>(p0, p1);
;   if (dow) {
;     if constexpr (KS == 0) { asm volatile("s_waitcnt vmcnt(0)" ::: "memory"); *reinterpret_cast<bf16x8*>(sd.k0) = st.ks0; }
;     else if constexpr (KS == 1) *reinterpret_cast<bf16x8*>(sd.k1) = st.ks1;
;     else if constexpr (KS == 2) *reinterpret_cast<bf16x8*>(sd.v0) = st.vs0;
;     else *reinterpret_cast<bf16x8*>(sd.v1) = st.vs1;
;   }
;   SBAR();
;   o[2] = MFMA32(pa, PKV(cur.l2, cur.h2), o[2]); SBAR(); sm1_chunk<KS * 4 + 2>(p0, p1); SM2_UNIT(2 * KS); SBAR();
;   o[3] = MFMA32(pa, PKV(cur.l3, cur.h3), o[3]); SBAR(); sm1_chunk<KS * 4 + 3>(p0, p1); SBAR();
;   if constexpr (!SAFE) { lacc = MFMA32(pa, ones, lacc); SBAR(); }
; }
; template <bool SAFE> ...
;   bf16x8 kb[8];
; #pragma unroll
;   for (int d0 = 0; d0 < 4; ++d0) { const int cb = (cb0 + d0 * 16 + hi * 8) * 2;
;     kb[2 * d0] = *reinterpret_cast<const bf16x8*>((const char*)Ks + KSWZ(r32, cb));
;     kb[2 * d0 + 1] = *reinterpret_cast<const bf16x8*>((const char*)Ks + KSWZ(32 + r32, cb)); }
;   VFrag fa, fb;
;   vfrag_issue<0>(fa, vb);
;   p0 = MFMA32(kb[0], qr[0], cinit); p1 = MFMA32(kb[1], qr[0], cinit);
; #pragma unroll
;   for (int d0 = 1; d0 < 4; ++d0) { p0 = MFMA32(kb[2 * d0], qr[d0], p0); p1 = MFMA32(kb[2 * d0 + 1], qr[d0], p1); }
;   SBAR();
;   unsigned a0, a1, b0, b1; ps = 0.f;
;   fused_ks<0, SAFE>(o, lacc, vb, fa, fb, p0, p1, ps, a0, a1, b0, b1, pa0, pa1, pa2, pa3, st, sd, dow, ones);
;   fused_ks<1, SAFE>(o, lacc, vb, fb, fa, p0, p1, ps, a0, a1, b0, b1, pa0, pa1, pa2, pa3, st, sd, dow, ones);
;   fused_ks<2, SAFE>(o, lacc, vb, fa, fb, p0, p1, ps, a0, a1, b0, b1, pa0, pa1, pa2, pa3, st, sd, dow, ones);
;   fused_ks<3, SAFE>(o, lacc, vb, fb, fa, p0, p1, ps, a0, a1, b0, b1, pa0, pa1, pa2, pa3, st, sd, dow, ones);
.LBB0_316:
	ds_read_b128 v[212:215], v77 offset:49152
	ds_read_b128 v[216:219], v77 offset:57344
	s_lshl_b32 s11, s10, 14
	s_add_i32 s8, s11, 0
	s_add_i32 s98, s7, 2
	s_min_i32 s98, s98, s64
	s_mul_i32 s98, s98, 0x60000
	s_add_u32 s98, s14, s98
	s_addc_u32 s99, s15, 0
	s_add_u32 s100, s98, 0x30000
	s_addc_u32 s101, s99, 0
	v_add_u32_e32 v173, s8, v209
	v_mov_b32_e32 v176, v180
	v_mfma_f32_32x32x16_bf16 v[112:127], v[68:71], v[132:135], v[80:95]
	v_mov_b32_e32 v180, v160
	v_add_u32_e32 v160, s8, v210
	v_lshl_add_u32 v194, s6, 14, v211
	s_lshl_b32 s9, s27, 14
	s_add_i32 s9, s9, 0
	s_mov_b32 s26, s27
	v_add_u32_e32 v76, s9, v207
	v_mov_b32_e32 v184, v170
	v_mfma_f32_32x32x16_bf16 v[96:111], v[72:75], v[132:135], v[80:95]
	ds_read_b128 v[68:71], v173 offset:49152
	ds_read_b128 v[72:75], v173 offset:57344
	v_mov_b32_e32 v177, v181
	v_mov_b32_e32 v172, v188
	v_mov_b32_e32 v181, v161
	v_add_u32_e32 v188, s9, v205
	v_add_u32_e32 v161, s9, v203
	v_add_u32_e32 v170, s9, v204
	s_waitcnt lgkmcnt(3)
	v_mfma_f32_32x32x16_bf16 v[112:127], v[212:215], v[136:139], v[112:127]
	ds_read_b128 v[212:215], v160 offset:49152
	v_mov_b32_e32 v185, v171
	s_waitcnt lgkmcnt(3)
	v_mfma_f32_32x32x16_bf16 v[96:111], v[216:219], v[136:139], v[96:111]
	ds_read_b128 v[216:219], v160 offset:57344
	v_mov_b32_e32 v173, v189
	v_add_u32_e32 v189, s9, v206
	v_add_u32_e32 v77, s9, v208
	s_waitcnt lgkmcnt(3)
	v_mfma_f32_32x32x16_bf16 v[112:127], v[68:71], v[140:143], v[112:127]
	ds_read_b64_tr_b16 v[220:221], v194 offset:0
	ds_read_b64_tr_b16 v[222:223], v194 offset:0x800
	s_waitcnt lgkmcnt(4)
	v_mfma_f32_32x32x16_bf16 v[96:111], v[72:75], v[140:143], v[96:111]
	s_waitcnt lgkmcnt(3)
	v_mfma_f32_32x32x16_bf16 v[112:127], v[212:215], v[144:147], v[112:127]
	ds_read_b64_tr_b16 v[212:213], v194 offset:0x200
	ds_read_b64_tr_b16 v[214:215], v194 offset:0xa00
	ds_read_b64_tr_b16 v[224:225], v194 offset:0x400
	ds_read_b64_tr_b16 v[226:227], v194 offset:0xc00
	ds_read_b64_tr_b16 v[228:229], v194 offset:0x600
	ds_read_b64_tr_b16 v[230:231], v194 offset:0xe00
	s_waitcnt lgkmcnt(7)
	v_mfma_f32_32x32x16_bf16 v[96:111], v[216:219], v[144:147], v[96:111]
	ds_read_b64_tr_b16 v[216:217], v194 offset:0x1000
	ds_read_b64_tr_b16 v[218:219], v194 offset:0x1800
	ds_read_b64_tr_b16 v[232:233], v194 offset:0x1200
	ds_read_b64_tr_b16 v[234:235], v194 offset:0x1a00
	ds_read_b64_tr_b16 v[236:237], v194 offset:0x1400
	ds_read_b64_tr_b16 v[238:239], v194 offset:0x1c00
	ds_read_b64_tr_b16 v[240:241], v194 offset:0x1600
	ds_read_b64_tr_b16 v[242:243], v194 offset:0x1e00
	s_waitcnt lgkmcnt(8)
	v_mfma_f32_32x32x16_bf16 v[48:63], v[180:183], v[220:223], v[48:63]
	s_nop 0
	v_exp_f32_e32 v112, v112
	v_exp_f32_e32 v113, v113
	v_mfma_f32_32x32x16_bf16 v[32:47], v[180:183], v[212:215], v[32:47]
	v_exp_f32_e32 v114, v114
	v_exp_f32_e32 v115, v115
	s_waitcnt vmcnt(3)
	ds_write_b128 v161, v[166:169] offset:49152
	global_load_dwordx4 v[166:169], v247, s[98:99] offset:1024
	v_mfma_f32_32x32x16_bf16 v[0:15], v[180:183], v[224:227], v[0:15]
	v_exp_f32_e32 v171, v116
	v_cvt_pk_bf16_f32 v160, v112, v113
	v_cvt_pk_bf16_f32 v161, v114, v115
	v_exp_f32_e32 v220, v117
	v_mfma_f32_32x32x16_bf16 v[16:31], v[180:183], v[228:231], v[16:31]
	v_exp_f32_e32 v221, v118
	v_exp_f32_e32 v222, v119
	v_mfma_f32_16x16x32_bf16 v[64:67], v[180:183], v[148:151], v[64:67]
	ds_read_b64_tr_b16 v[112:113], v194 offset:0x2000
	ds_read_b64_tr_b16 v[114:115], v194 offset:0x2800
	ds_read_b64_tr_b16 v[116:117], v194 offset:0x2200
	ds_read_b64_tr_b16 v[118:119], v194 offset:0x2a00
	ds_read_b64_tr_b16 v[248:249], v194 offset:0x2400
	ds_read_b64_tr_b16 v[250:251], v194 offset:0x2c00
	ds_read_b64_tr_b16 v[212:213], v194 offset:0x2600
	ds_read_b64_tr_b16 v[214:215], v194 offset:0x2e00
	s_waitcnt lgkmcnt(8)
	v_mfma_f32_32x32x16_bf16 v[48:63], v[184:187], v[216:219], v[48:63]
	v_cvt_pk_bf16_f32 v182, v171, v220
	v_cvt_pk_bf16_f32 v183, v221, v222
	v_exp_f32_e32 v120, v120
	v_exp_f32_e32 v121, v121
	v_mfma_f32_32x32x16_bf16 v[32:47], v[184:187], v[232:235], v[32:47]
	v_exp_f32_e32 v122, v122
	v_exp_f32_e32 v123, v123
	s_waitcnt vmcnt(3)
	ds_write_b128 v170, v[162:165] offset:49152
	global_load_dwordx4 v[162:165], v247, s[100:101] offset:1024
	v_mfma_f32_32x32x16_bf16 v[0:15], v[184:187], v[236:239], v[0:15]
	v_exp_f32_e32 v180, v124
	v_exp_f32_e32 v181, v125
	v_cvt_pk_bf16_f32 v170, v120, v121
	v_cvt_pk_bf16_f32 v171, v122, v123
	v_mfma_f32_32x32x16_bf16 v[16:31], v[184:187], v[240:243], v[16:31]
	v_exp_f32_e32 v220, v126
	v_exp_f32_e32 v221, v127
	v_mfma_f32_16x16x32_bf16 v[64:67], v[184:187], v[148:151], v[64:67]
	s_waitcnt lgkmcnt(0)
	s_barrier
; #define SBAR() __builtin_amdgcn_sched_barrier(0)
; template <int KS, bool SAFE> __device__ __forceinline__ void fused_ks(f32x16* o, f32x16& lacc, int vb, const VFrag& cur, VFrag& nxt, f32x16& p0, f32x16& p1, float& ps, ...
;   if constexpr (KS < 3) { vfrag_issue<KS + 1>(nxt, vb); asm volatile("s_waitcnt lgkmcnt(8)" ::: "memory"); }
;   else asm volatile("s_waitcnt lgkmcnt(0)" ::: "memory");
;   const bf16x8 pa = (KS == 0) ? pa0 : (KS == 1) ? pa1 : (KS == 2) ? pa2 : pa3;
;   SBAR();
;   o[0] = MFMA32(pa, PKV(cur.l0, cur.h0), o[0]); SBAR(); sm1_chunk<KS * 4 + 0>(p0, p1); if constexpr (KS > 0) SM2_UNIT(2 * KS - 1); SBAR();
;   o[1] = MFMA32(pa, PKV(cur.l1, cur.h1), o[1]); SBAR(); sm1_chunk<KS * 4 + 1>(p0, p1);
;   if (dow) {
;     if constexpr (KS == 0) { asm volatile("s_waitcnt vmcnt(0)" ::: "memory"); *reinterpret_cast<bf16x8*>(sd.k0) = st.ks0; }
;     else if constexpr (KS == 1) *reinterpret_cast<bf16x8*>(sd.k1) = st.ks1;
;     else if constexpr (KS == 2) *reinterpret_cast<bf16x8*>(sd.v0) = st.vs0;
;     else *reinterpret_cast<bf16x8*>(sd.v1) = st.vs1;
;   }
;   SBAR();
;   o[2] = MFMA32(pa, PKV(cur.l2, cur.h2), o[2]); SBAR(); sm1_chunk<KS * 4 + 2>(p0, p1); SM2_UNIT(2 * KS); SBAR();
;   o[3] = MFMA32(pa, PKV(cur.l3, cur.h3), o[3]); SBAR(); sm1_chunk<KS * 4 + 3>(p0, p1); SBAR();
;   if constexpr (!SAFE) { lacc = MFMA32(pa, ones, lacc); SBAR(); }
; }
; template <bool SAFE>
; __device__ __forceinline__ void diff_core(const bf16* __restrict__ Kh, const bf16* __restrict__ Vh, const int NT, const bf16x8* qr, char* lds,
;                                           const int wid, const int lane_unused, f32x16* o, f32x16& lacc, float& l_reg) {
;     ...
;   for (int j = 1; j < NT; ++j) {
;     const bool dow = true;
;     const bf16* Kc = (const bf16*)((const char*)K_lds + bc * SHM_K);
;     StgDst sd;
;     sd.v0 = (char*)V_lds + bn * SHM_V + vst0; sd.v1 = (char*)V_lds + bn * SHM_V + vst1;
;     sd.k0 = (char*)K_lds + bn * SHM_K + kw0;  sd.k1 = (char*)K_lds + bn * SHM_K + kw1;
;     tile_step<SAFE>(o, lacc, Kc, vb0 + bp * SHM_V, qr, rk, hi, cb0, p0, p1, cinit, ps, pa0, pa1, pa2, pa3, sr_[0], sd, dow, ones);
;     SLOAD(0, min(j + 2, NT - 1) * 64);
;     SBAR();
;     if constexpr (SAFE) FIXUP(Kc, false);
;     asm volatile("s_waitcnt lgkmcnt(0)" ::: "memory"); __builtin_amdgcn_s_barrier(); asm volatile("" ::: "memory");
;     const int t_ = bp; bp = bc; bc = bn; bn = t_;
	ds_read_b128 v[68:71], v76 offset:49152
	ds_read_b128 v[72:75], v76 offset:57344
	ds_read_b64_tr_b16 v[120:121], v194 offset:0x3000
	ds_read_b64_tr_b16 v[122:123], v194 offset:0x3800
	ds_read_b64_tr_b16 v[124:125], v194 offset:0x3200
	ds_read_b64_tr_b16 v[126:127], v194 offset:0x3a00
	ds_read_b64_tr_b16 v[252:253], v194 offset:0x3400
	ds_read_b64_tr_b16 v[254:255], v194 offset:0x3c00
	ds_read_b64_tr_b16 v[216:217], v194 offset:0x3600
	ds_read_b64_tr_b16 v[218:219], v194 offset:0x3e00
	v_mfma_f32_32x32x16_bf16 v[48:63], v[176:179], v[112:115], v[48:63]
	v_cvt_pk_bf16_f32 v186, v180, v181
	v_cvt_pk_bf16_f32 v187, v220, v221
	v_exp_f32_e32 v96, v96
	v_exp_f32_e32 v97, v97
	v_mfma_f32_32x32x16_bf16 v[32:47], v[176:179], v[116:119], v[32:47]
	v_exp_f32_e32 v98, v98
	v_exp_f32_e32 v99, v99
	s_waitcnt vmcnt(3)
	ds_write_b128 v188, v[156:159]
	global_load_dwordx4 v[156:159], v247, s[98:99] offset:2048
	v_mfma_f32_32x32x16_bf16 v[0:15], v[176:179], v[248:251], v[0:15]
	v_cvt_pk_bf16_f32 v180, v96, v97
	v_cvt_pk_bf16_f32 v181, v98, v99
	v_exp_f32_e32 v100, v100
	v_exp_f32_e32 v101, v101
	v_mfma_f32_32x32x16_bf16 v[16:31], v[176:179], v[212:215], v[16:31]
	v_exp_f32_e32 v96, v102
	v_exp_f32_e32 v97, v103
	v_mfma_f32_16x16x32_bf16 v[64:67], v[176:179], v[148:151], v[64:67]
	s_waitcnt lgkmcnt(0)
	v_mfma_f32_32x32x16_bf16 v[48:63], v[172:175], v[120:123], v[48:63]
	v_cvt_pk_bf16_f32 v178, v100, v101
	v_cvt_pk_bf16_f32 v179, v96, v97
	v_exp_f32_e32 v98, v104
	v_exp_f32_e32 v99, v105
	v_mfma_f32_32x32x16_bf16 v[32:47], v[172:175], v[124:127], v[32:47]
	v_exp_f32_e32 v96, v106
	v_exp_f32_e32 v97, v107
	s_waitcnt vmcnt(3)
	ds_write_b128 v189, v[152:155]
	global_load_dwordx4 v[152:155], v247, s[100:101] offset:2048
	v_mfma_f32_32x32x16_bf16 v[0:15], v[172:175], v[252:255], v[0:15]
	v_cvt_pk_bf16_f32 v188, v98, v99
	v_cvt_pk_bf16_f32 v189, v96, v97
	v_exp_f32_e32 v100, v108
	v_exp_f32_e32 v101, v109
	v_mfma_f32_32x32x16_bf16 v[16:31], v[172:175], v[216:219], v[16:31]
	v_exp_f32_e32 v96, v110
	v_exp_f32_e32 v97, v111
	v_mfma_f32_16x16x32_bf16 v[64:67], v[172:175], v[148:151], v[64:67]
	v_cvt_pk_bf16_f32 v174, v100, v101
	v_cvt_pk_bf16_f32 v175, v96, v97
	s_add_i32 s7, s7, 1
	s_mov_b32 s27, s6
	s_mov_b32 s6, s10
	s_cmp_lg_u32 s55, s7
	s_mov_b32 s10, s26
	s_cbranch_scc1 .LBB0_316
; #define MFMA32(a, b, c) __builtin_amdgcn_mfma_f32_32x32x16_bf16(a, b, c, 0, 0, 0)
; template <bool SAFE>
; __device__ __forceinline__ void diff_core(const bf16* __restrict__ Kh, const bf16* __restrict__ Vh, const int NT, const bf16x8* qr, char* lds,
;                                           const int wid, const int lane_unused, f32x16* o, f32x16& lacc, float& l_reg) {
;     ...
;   pv_d0(o, vb0 + bp * SHM_V, pa0, pa1, pa2, pa3);
;   if constexpr (!SAFE) {
;     lacc = MFMA32(pa0, ones, lacc); lacc = MFMA32(pa1, ones, lacc); lacc = MFMA32(pa2, ones, lacc); lacc = MFMA32(pa3, ones, lacc); }
; __device__ __forceinline__ void diff_attn_item(const bf16* __restrict__ qkv, bf16* __restrict__ mix, const float* __restrict__ dg,
;                                int tok0  , int key0  , int seq, int head, float lam, float oscale, const int W) {
;     ...
;     bool bad = (FORCE_SAFE != 0);
; #pragma unroll
;     for (int r = 0; r < 16; ++r) bad = bad || !(lacc[r] < 1.0e30f);
;     if (lane == 0) flag_l[wid] = __any(bad) ? 1 : 0;
	s_waitcnt vmcnt(0)
	v_add_u32_e32 v168, s11, v211
	ds_read_b64_tr_b16 v[80:81], v168 offset:0
	ds_read_b64_tr_b16 v[82:83], v168 offset:0x800
	ds_read_b64_tr_b16 v[84:85], v168 offset:0x1000
	ds_read_b64_tr_b16 v[86:87], v168 offset:0x1800
	ds_read_b64_tr_b16 v[88:89], v168 offset:0x2000
	ds_read_b64_tr_b16 v[90:91], v168 offset:0x2800
	ds_read_b64_tr_b16 v[92:93], v168 offset:0x3000
	ds_read_b64_tr_b16 v[94:95], v168 offset:0x3800
	s_waitcnt lgkmcnt(0)
	s_waitcnt vmcnt(0)
	v_mov_b32_e32 v162, v182
	v_mov_b32_e32 v163, v183
	v_mov_b32_e32 v172, v186
	v_mov_b32_e32 v173, v187
	v_mov_b32_e32 v182, v178
	v_mov_b32_e32 v183, v179
	v_mov_b32_e32 v190, v174
	v_mov_b32_e32 v191, v175
	ds_read_b64_tr_b16 v[96:97], v168 offset:0x200
	ds_read_b64_tr_b16 v[98:99], v168 offset:0xa00
	ds_read_b64_tr_b16 v[100:101], v168 offset:0x1200
	ds_read_b64_tr_b16 v[102:103], v168 offset:0x1a00
	ds_read_b64_tr_b16 v[104:105], v168 offset:0x2200
	ds_read_b64_tr_b16 v[106:107], v168 offset:0x2a00
	ds_read_b64_tr_b16 v[108:109], v168 offset:0x3200
	ds_read_b64_tr_b16 v[110:111], v168 offset:0x3a00
	s_waitcnt lgkmcnt(0)
	ds_read_b64_tr_b16 v[112:113], v168 offset:0x400
	ds_read_b64_tr_b16 v[114:115], v168 offset:0xc00
	ds_read_b64_tr_b16 v[116:117], v168 offset:0x1400
	ds_read_b64_tr_b16 v[118:119], v168 offset:0x1c00
	ds_read_b64_tr_b16 v[120:121], v168 offset:0x2400
	ds_read_b64_tr_b16 v[122:123], v168 offset:0x2c00
	ds_read_b64_tr_b16 v[124:125], v168 offset:0x3400
	ds_read_b64_tr_b16 v[126:127], v168 offset:0x3c00
	s_waitcnt lgkmcnt(0)
	ds_read_b64_tr_b16 v[152:153], v168 offset:0x600
	ds_read_b64_tr_b16 v[154:155], v168 offset:0xe00
	ds_read_b64_tr_b16 v[156:157], v168 offset:0x1600
	ds_read_b64_tr_b16 v[158:159], v168 offset:0x1e00
	ds_read_b64_tr_b16 v[164:165], v168 offset:0x2600
	ds_read_b64_tr_b16 v[166:167], v168 offset:0x2e00
	ds_read_b64_tr_b16 v[174:175], v168 offset:0x3600
	ds_read_b64_tr_b16 v[176:177], v168 offset:0x3e00
	s_waitcnt lgkmcnt(0)
	v_mfma_f32_16x16x32_bf16 v[64:67], v[160:163], v[148:151], v[64:67]
	v_cmp_eq_u32_e32 vcc, 0, v200
	v_mfma_f32_32x32x16_bf16 v[48:63], v[160:163], v[80:83], v[48:63]
	v_mfma_f32_32x32x16_bf16 v[32:47], v[160:163], v[96:99], v[32:47]
	v_mfma_f32_32x32x16_bf16 v[0:15], v[160:163], v[112:115], v[0:15]
	v_mfma_f32_32x32x16_bf16 v[16:31], v[160:163], v[152:155], v[16:31]
	v_mfma_f32_16x16x32_bf16 v[64:67], v[170:173], v[148:151], v[64:67]
	v_mfma_f32_32x32x16_bf16 v[48:63], v[170:173], v[84:87], v[48:63]
	v_mfma_f32_32x32x16_bf16 v[32:47], v[170:173], v[100:103], v[32:47]
	v_mfma_f32_32x32x16_bf16 v[0:15], v[170:173], v[116:119], v[0:15]
	v_mfma_f32_32x32x16_bf16 v[16:31], v[170:173], v[156:159], v[16:31]
	v_mfma_f32_16x16x32_bf16 v[64:67], v[180:183], v[148:151], v[64:67]
	v_mfma_f32_32x32x16_bf16 v[48:63], v[180:183], v[88:91], v[48:63]
	v_mfma_f32_32x32x16_bf16 v[32:47], v[180:183], v[104:107], v[32:47]
	v_mfma_f32_32x32x16_bf16 v[0:15], v[180:183], v[120:123], v[0:15]
	v_mfma_f32_32x32x16_bf16 v[16:31], v[180:183], v[164:167], v[16:31]
	v_mfma_f32_16x16x32_bf16 v[64:67], v[188:191], v[148:151], v[64:67]
	v_mfma_f32_32x32x16_bf16 v[48:63], v[188:191], v[92:95], v[48:63]
	v_mfma_f32_32x32x16_bf16 v[32:47], v[188:191], v[108:111], v[32:47]
	v_mfma_f32_32x32x16_bf16 v[0:15], v[188:191], v[124:127], v[0:15]
	v_mfma_f32_32x32x16_bf16 v[16:31], v[188:191], v[174:177], v[16:31]
	v_and_b32_e32 v248, 15, v200
	v_lshrrev_b32_e32 v249, 4, v200
	v_and_b32_e32 v250, 1, v200
	v_lshlrev_b32_e32 v249, 4, v249
	v_lshl_add_u32 v249, v250, 6, v249
	v_add_u32_e32 v249, s62, v249
	v_cmp_gt_u32_e64 s[98:99], 2, v248
	v_lshl_add_u32 v250, v198, 4, s62
	s_nop 7
	s_and_saveexec_b64 s[100:101], s[98:99]
	ds_write_b128 v249, v[64:67]
	s_mov_b64 exec, s[100:101]
	s_waitcnt lgkmcnt(0)
	ds_read_b128 v[64:67], v250
	ds_read_b128 v[68:71], v250 offset:32
	ds_read_b128 v[72:75], v250 offset:64
	ds_read_b128 v[76:79], v250 offset:96
	s_waitcnt lgkmcnt(0)
	s_and_saveexec_b64 s[10:11], vcc
	s_cbranch_execz .LBB0_319
	s_nop 5
	v_cmp_ngt_f32_e32 vcc, s44, v64
	v_cmp_ngt_f32_e64 s[6:7], s44, v65
	s_or_b64 s[6:7], vcc, s[6:7]
	v_cmp_ngt_f32_e32 vcc, s44, v66
	s_or_b64 s[6:7], s[6:7], vcc
	v_cmp_ngt_f32_e32 vcc, s44, v67
	s_or_b64 s[6:7], s[6:7], vcc
	v_cmp_ngt_f32_e32 vcc, s44, v68
	s_or_b64 s[6:7], s[6:7], vcc
	v_cmp_ngt_f32_e32 vcc, s44, v69
	s_or_b64 s[6:7], s[6:7], vcc
	v_cmp_ngt_f32_e32 vcc, s44, v70
	s_or_b64 s[6:7], s[6:7], vcc
	v_cmp_ngt_f32_e32 vcc, s44, v71
	s_or_b64 s[6:7], s[6:7], vcc
	v_cmp_ngt_f32_e32 vcc, s44, v72
	s_or_b64 s[6:7], s[6:7], vcc
	v_cmp_ngt_f32_e32 vcc, s44, v73
	s_or_b64 s[6:7], s[6:7], vcc
	v_cmp_ngt_f32_e32 vcc, s44, v74
	s_or_b64 s[6:7], s[6:7], vcc
	v_cmp_ngt_f32_e32 vcc, s44, v75
	s_or_b64 s[6:7], s[6:7], vcc
	v_cmp_ngt_f32_e32 vcc, s44, v76
	s_or_b64 s[6:7], s[6:7], vcc
	v_cmp_ngt_f32_e32 vcc, s44, v77
	s_or_b64 s[6:7], s[6:7], vcc
	v_cmp_ngt_f32_e32 vcc, s44, v78
	s_or_b64 s[6:7], s[6:7], vcc
	v_cmp_ngt_f32_e32 vcc, s44, v79
	s_or_b64 s[6:7], s[6:7], vcc
	v_cndmask_b32_e64 v80, 0, 1, s[6:7]
	v_cmp_ne_u32_e32 vcc, 0, v80
	s_cmp_lg_u64 vcc, 0
	s_cselect_b64 s[6:7], -1, 0
	v_cndmask_b32_e64 v80, 0, 1, s[6:7]
	v_readlane_b32 s6, v246, 17
	s_nop 1
	v_mov_b32_e32 v81, s6
	ds_write_b32 v81, v80
